# attention loop: 16 v_pk_fma_f32 (score scaling) rewritten as scalar v_fma_f32 pairs (guide 7.5: packed f32 beside MFMAs)
# baseline (speedup 1.0000x reference)
.LBB0_2061:
	s_mov_b64 s[10:11], -1
	s_and_b64 vcc, exec, s[6:7]
	s_cbranch_vccz .LBB0_2055
	s_ashr_i32 s58, s9, 7
	s_lshl_b32 s10, s9, 8
	s_lshl_b32 s7, s58, 12
	s_and_b32 s10, s10, 0xf00
	s_or_b32 s30, s7, s10
	s_bfe_u32 s6, s9, 0x10006
	s_ashr_i32 s31, s30, 31
	s_mul_i32 s10, s30, 0xc00
	s_mul_hi_i32 s7, s30, 0xc00
	s_add_u32 s10, s82, s10
	s_addc_u32 s7, s83, s7
	s_lshl_b32 s9, s9, 3
	s_lshl_b32 s11, s6, 9
	s_and_b32 s9, s9, 0x180
	s_or_b32 s50, s11, s9
	s_lshl_b32 s9, s50, 1
	s_add_u32 s10, s10, s9
	s_addc_u32 s11, s7, 0
	s_mul_hi_i32 s57, s58, 0x220000
	s_mul_i32 s58, s58, 0x220000
	s_add_u32 s7, s44, s58
	s_addc_u32 s9, s71, s57
	s_lshl_b32 s59, s6, 8
	s_add_u32 s6, s7, s59
	s_addc_u32 s7, s9, 0
	s_add_u32 s9, s24, s58
	s_addc_u32 s12, s25, s57
	s_add_u32 s34, s9, s59
	s_addc_u32 s35, s12, 0
	global_load_dwordx4 v[2:5], v199, s[34:35]
	global_load_dwordx4 v[6:9], v200, s[34:35]
	global_load_dwordx4 v[10:13], v199, s[6:7]
	global_load_dwordx4 v[14:17], v200, s[6:7]
	v_mov_b32_e32 v193, v179
	v_lshl_add_u64 v[18:19], s[10:11], 0, v[192:193]
	v_mov_b32_e32 v195, v179
	v_lshl_add_u64 v[18:19], v[18:19], 0, v[194:195]
	global_load_dwordx4 v[126:129], v[18:19], off
	global_load_dwordx4 v[122:125], v[18:19], off offset:32
	global_load_dwordx4 v[118:121], v[18:19], off offset:64
	global_load_dwordx4 v[114:117], v[18:19], off offset:96
	global_load_dwordx4 v[110:113], v[18:19], off offset:128
	global_load_dwordx4 v[106:109], v[18:19], off offset:160
	global_load_dwordx4 v[102:105], v[18:19], off offset:192
	global_load_dwordx4 v[98:101], v[18:19], off offset:224
	s_waitcnt vmcnt(0)
	s_mov_b32 s9, s8
	s_mov_b32 s10, s8
	s_mov_b32 s11, s8
	s_mov_b32 s12, s8
	s_mov_b32 s13, s8
	s_mov_b32 s14, s8
	s_mov_b32 s15, s8
	s_mov_b32 s16, s8
	s_mov_b32 s17, s8
	s_mov_b32 s18, s8
	s_mov_b32 s19, s8
	s_mov_b32 s20, s8
	s_mov_b32 s21, s8
	s_mov_b32 s22, s8
	s_mov_b32 s23, s8
	s_mov_b32 s51, 1
	v_mov_b32_e32 v191, 0
	s_waitcnt vmcnt(11)
	ds_write_b128 v201, v[2:5]
	s_waitcnt vmcnt(10)
	ds_write_b128 v202, v[6:9]
	s_waitcnt vmcnt(9)
	ds_write_b128 v203, v[10:13] offset:32768
	s_waitcnt vmcnt(8)
	ds_write_b128 v204, v[14:17] offset:32768
	s_waitcnt lgkmcnt(0)
	s_barrier
	ds_read_b128 v[2:5], v205 offset:32768
	ds_read_b128 v[6:9], v205 offset:40960
	s_waitcnt vmcnt(7) lgkmcnt(1)
	v_mfma_f32_32x32x16_bf16 v[18:33], v[2:5], v[126:129], 0
	s_waitcnt lgkmcnt(0)
	v_mfma_f32_32x32x16_bf16 v[34:49], v[6:9], v[126:129], 0
	ds_read_b128 v[2:5], v206 offset:32768
	ds_read_b128 v[6:9], v206 offset:40960
	s_waitcnt vmcnt(6) lgkmcnt(1)
	v_mfma_f32_32x32x16_bf16 v[18:33], v[2:5], v[122:125], v[18:33]
	s_waitcnt lgkmcnt(0)
	v_mfma_f32_32x32x16_bf16 v[34:49], v[6:9], v[122:125], v[34:49]
	ds_read_b128 v[2:5], v207 offset:32768
	ds_read_b128 v[6:9], v207 offset:40960
	s_waitcnt vmcnt(5) lgkmcnt(1)
	v_mfma_f32_32x32x16_bf16 v[18:33], v[2:5], v[118:121], v[18:33]
	s_waitcnt lgkmcnt(0)
	v_mfma_f32_32x32x16_bf16 v[34:49], v[6:9], v[118:121], v[34:49]
	ds_read_b128 v[2:5], v208 offset:32768
	ds_read_b128 v[6:9], v208 offset:40960
	s_waitcnt vmcnt(4) lgkmcnt(1)
	v_mfma_f32_32x32x16_bf16 v[18:33], v[2:5], v[114:117], v[18:33]
	s_waitcnt lgkmcnt(0)
	v_mfma_f32_32x32x16_bf16 v[34:49], v[6:9], v[114:117], v[34:49]
	ds_read_b128 v[2:5], v209 offset:32768
	ds_read_b128 v[6:9], v209 offset:40960
	s_waitcnt vmcnt(3) lgkmcnt(1)
	v_mfma_f32_32x32x16_bf16 v[18:33], v[2:5], v[110:113], v[18:33]
	s_waitcnt lgkmcnt(0)
	v_mfma_f32_32x32x16_bf16 v[34:49], v[6:9], v[110:113], v[34:49]
	ds_read_b128 v[2:5], v210 offset:32768
	ds_read_b128 v[6:9], v210 offset:40960
	global_load_dwordx4 v[50:53], v215, s[34:35]
	global_load_dwordx4 v[54:57], v214, s[34:35]
	global_load_dwordx4 v[58:61], v214, s[6:7]
	global_load_dwordx4 v[62:65], v215, s[6:7]
	ds_read_b128 v[66:69], v212 offset:40960
	s_waitcnt vmcnt(6) lgkmcnt(2)
	v_mfma_f32_32x32x16_bf16 v[18:33], v[2:5], v[106:109], v[18:33]
	ds_read_b128 v[2:5], v211 offset:32768
	s_waitcnt lgkmcnt(2)
	v_mfma_f32_32x32x16_bf16 v[34:49], v[6:9], v[106:109], v[34:49]
	ds_read_b128 v[6:9], v211 offset:40960
	s_waitcnt vmcnt(5) lgkmcnt(1)
	v_mfma_f32_32x32x16_bf16 v[18:33], v[2:5], v[102:105], v[18:33]
	ds_read_b128 v[2:5], v212 offset:32768
	global_load_dwordx4 v[130:133], v216, s[34:35]
	global_load_dwordx4 v[138:141], v216, s[6:7]
	global_load_dwordx4 v[134:137], v217, s[34:35]
	global_load_dwordx4 v[142:145], v217, s[6:7]
	s_waitcnt vmcnt(4)
	s_waitcnt vmcnt(6)
	ds_write_b128 v201, v[54:57] offset:16384
	ds_write_b128 v202, v[50:53] offset:16384
	s_waitcnt vmcnt(5)
	ds_write_b128 v203, v[58:61] offset:49152
	s_waitcnt vmcnt(4)
	ds_write_b128 v204, v[62:65] offset:49152
	s_waitcnt lgkmcnt(5)
	v_mfma_f32_32x32x16_bf16 v[34:49], v[6:9], v[102:105], v[34:49]
	s_waitcnt lgkmcnt(0)
	s_barrier
	v_mfma_f32_32x32x16_bf16 v[18:33], v[2:5], v[98:101], v[18:33]
	v_mov_b64_e32 v[2:3], s[8:9]
	v_mov_b64_e32 v[16:17], s[22:23]
	v_mov_b64_e32 v[4:5], s[10:11]
	v_mov_b64_e32 v[6:7], s[12:13]
	v_mov_b64_e32 v[8:9], s[14:15]
	v_mov_b64_e32 v[10:11], s[16:17]
	v_mov_b64_e32 v[12:13], s[18:19]
	v_mfma_f32_32x32x16_bf16 v[34:49], v[66:69], v[98:101], v[34:49]
	s_nop 3
	v_max_f32_e32 v66, v19, v19
	v_max_f32_e32 v67, v18, v18
	v_max_f32_e32 v66, v67, v66
	v_max3_f32 v66, v66, v20, v21
	v_max3_f32 v66, v66, v22, v23
	v_max3_f32 v66, v66, v24, v25
	v_max3_f32 v66, v66, v26, v27
	v_max3_f32 v66, v66, v28, v29
	v_max3_f32 v66, v66, v30, v31
	v_max3_f32 v50, v66, v32, v33
	v_max3_f32 v50, v50, v34, v35
	v_max3_f32 v50, v50, v36, v37
	v_max3_f32 v50, v50, v38, v39
	v_max3_f32 v50, v50, v40, v41
	v_max3_f32 v50, v50, v42, v43
	v_max3_f32 v50, v50, v44, v45
	v_max3_f32 v50, v50, v46, v47
	v_max3_f32 v50, v50, v48, v49
	v_mov_b32_e32 v51, v50
	s_nop 1
	v_permlane32_swap_b32_e32 v50, v51
	v_max_f32_e32 v51, v51, v51
	v_max_f32_e32 v50, v50, v50
	v_max_f32_e32 v50, v50, v51
	v_add_f32_e32 v51, 0x7149f2ca, v50
	v_cmp_ge_f32_e32 vcc, s37, v51
	s_cmp_eq_u64 vcc, exec
	v_max_f32_e32 v50, 0xf149f2ca, v50
	s_cselect_b64 vcc, -1, 0
	v_sub_f32_e32 v51, 0xf149f2ca, v50
	v_cndmask_b32_e32 v166, v50, v213, vcc
	v_mul_f32_e32 v51, 0x3e0293ee, v51
	v_mul_f32_e32 v50, 0xbe0293ee, v166
	v_exp_f32_e32 v51, v51
	v_mov_b32_e32 v52, v50
	v_fmamk_f32 v18, v18, 0x3e0293ee, v50
	v_fmamk_f32 v19, v19, 0x3e0293ee, v50
	v_fmamk_f32 v20, v20, 0x3e0293ee, v50
	v_fmamk_f32 v21, v21, 0x3e0293ee, v50
	v_fmamk_f32 v22, v22, 0x3e0293ee, v50
	v_fmamk_f32 v23, v23, 0x3e0293ee, v50
	v_fmamk_f32 v24, v24, 0x3e0293ee, v50
	v_fmamk_f32 v25, v25, 0x3e0293ee, v50
	v_fmamk_f32 v26, v26, 0x3e0293ee, v50
	v_fmamk_f32 v27, v27, 0x3e0293ee, v50
	v_fmamk_f32 v28, v28, 0x3e0293ee, v50
	v_fmamk_f32 v29, v29, 0x3e0293ee, v50
	v_fmamk_f32 v30, v30, 0x3e0293ee, v50
	v_fmamk_f32 v31, v31, 0x3e0293ee, v50
	v_fmamk_f32 v32, v32, 0x3e0293ee, v50
	v_fmac_f32_e32 v52, 0x3e0293ee, v33
	v_exp_f32_e32 v177, v18
	v_exp_f32_e32 v223, v19
	v_exp_f32_e32 v163, v20
	v_exp_f32_e32 v220, v21
	v_exp_f32_e32 v164, v22
	v_exp_f32_e32 v176, v23
	v_exp_f32_e32 v165, v24
	v_exp_f32_e32 v175, v25
	v_exp_f32_e32 v172, v26
	v_exp_f32_e32 v174, v27
	v_exp_f32_e32 v171, v28
	v_exp_f32_e32 v173, v29
	v_exp_f32_e32 v168, v30
	v_exp_f32_e32 v170, v31
	v_exp_f32_e32 v167, v32
	v_exp_f32_e32 v169, v52
	s_or_b32 s6, s58, s59
	v_mov_b64_e32 v[14:15], s[20:21]
	s_add_u32 s10, s52, s6
	v_fma_f32 v152, v48, s28, v50
	v_fma_f32 v153, v49, s28, v50
	v_fma_f32 v158, v46, s28, v50
	v_fma_f32 v159, v47, s28, v50
	v_fma_f32 v160, v44, s28, v50
	v_fma_f32 v161, v45, s28, v50
	v_fma_f32 v146, v42, s28, v50
	v_fma_f32 v147, v43, s28, v50
	v_fma_f32 v148, v40, s28, v50
	v_fma_f32 v149, v41, s28, v50
	v_fma_f32 v150, v38, s28, v50
	v_fma_f32 v151, v39, s28, v50
	v_fma_f32 v154, v36, s28, v50
	v_fma_f32 v155, v37, s28, v50
	v_fma_f32 v156, v34, s28, v50
	v_fma_f32 v157, v35, s28, v50
	v_cndmask_b32_e64 v193, v51, 1.0, vcc
	v_mov_b64_e32 v[64:65], v[16:17]
	v_mov_b64_e32 v[48:49], v[16:17]
	v_mov_b64_e32 v[32:33], v[16:17]
	s_addc_u32 s11, s53, s57
	v_mov_b64_e32 v[62:63], v[14:15]
	v_mov_b64_e32 v[60:61], v[12:13]
	v_mov_b64_e32 v[58:59], v[10:11]
	v_mov_b64_e32 v[56:57], v[8:9]
	v_mov_b64_e32 v[54:55], v[6:7]
	v_mov_b64_e32 v[52:53], v[4:5]
	v_mov_b64_e32 v[50:51], v[2:3]
	v_mov_b64_e32 v[46:47], v[14:15]
	v_mov_b64_e32 v[44:45], v[12:13]
	v_mov_b64_e32 v[42:43], v[10:11]
	v_mov_b64_e32 v[40:41], v[8:9]
	v_mov_b64_e32 v[38:39], v[6:7]
	v_mov_b64_e32 v[36:37], v[4:5]
	v_mov_b64_e32 v[34:35], v[2:3]
	v_mov_b64_e32 v[30:31], v[14:15]
	v_mov_b64_e32 v[28:29], v[12:13]
	v_mov_b64_e32 v[26:27], v[10:11]
	v_mov_b64_e32 v[24:25], v[8:9]
	v_mov_b64_e32 v[22:23], v[6:7]
	v_mov_b64_e32 v[20:21], v[4:5]
	v_mov_b64_e32 v[18:19], v[2:3]

.LBB0_2073:
	v_cndmask_b32_e64 v166, v163, v220, s[6:7]
	v_mul_f32_e32 v152, 0xbe0293ee, v166
	v_mov_b32_e32 v153, v152
	v_fmamk_f32 v82, v82, 0x3e0293ee, v152
	v_fmamk_f32 v83, v83, 0x3e0293ee, v152
	v_fmamk_f32 v84, v84, 0x3e0293ee, v152
	v_fmamk_f32 v85, v85, 0x3e0293ee, v152
	v_fmamk_f32 v86, v86, 0x3e0293ee, v152
	v_fmamk_f32 v87, v87, 0x3e0293ee, v152
	v_fmamk_f32 v88, v88, 0x3e0293ee, v152
	v_fmamk_f32 v89, v89, 0x3e0293ee, v152
	v_fmamk_f32 v90, v90, 0x3e0293ee, v152
	v_fmamk_f32 v91, v91, 0x3e0293ee, v152
	v_fmamk_f32 v92, v92, 0x3e0293ee, v152
	v_fmamk_f32 v93, v93, 0x3e0293ee, v152
	v_fmamk_f32 v94, v94, 0x3e0293ee, v152
	v_fmamk_f32 v95, v95, 0x3e0293ee, v152
	v_fmamk_f32 v96, v96, 0x3e0293ee, v152
	v_fmac_f32_e32 v153, 0x3e0293ee, v97
	v_exp_f32_e32 v177, v82
	v_exp_f32_e32 v223, v83
	v_exp_f32_e32 v163, v84
	v_exp_f32_e32 v220, v85
	v_exp_f32_e32 v164, v86
	v_exp_f32_e32 v176, v87
	v_exp_f32_e32 v165, v88
	v_exp_f32_e32 v175, v89
	v_exp_f32_e32 v172, v90
	v_exp_f32_e32 v174, v91
	v_exp_f32_e32 v171, v92
	v_exp_f32_e32 v173, v93
	v_exp_f32_e32 v168, v94
	v_exp_f32_e32 v170, v95
	v_exp_f32_e32 v167, v96
	v_exp_f32_e32 v169, v153
	v_fma_f32 v156, v66, s28, v152
	v_fma_f32 v157, v67, s28, v152
	v_add_f32_e32 v66, v195, v218
	s_add_i32 s51, s51, 2
	v_fmac_f32_e32 v66, v193, v191
	v_add_f32_e32 v191, v221, v222
	s_add_u32 s10, s10, 0x10000
	v_fma_f32 v154, v68, s28, v152
	v_fma_f32 v155, v69, s28, v152
	v_fma_f32 v150, v70, s28, v152
	v_fma_f32 v151, v71, s28, v152
	v_fma_f32 v148, v72, s28, v152
	v_fma_f32 v149, v73, s28, v152
	v_fma_f32 v146, v74, s28, v152
	v_fma_f32 v147, v75, s28, v152
	v_fma_f32 v160, v76, s28, v152
	v_fma_f32 v161, v77, s28, v152
	v_fma_f32 v158, v78, s28, v152
	v_fma_f32 v159, v79, s28, v152
	v_fma_f32 v153, v81, s28, v152
	v_fma_f32 v152, v80, s28, v152
	v_fmac_f32_e32 v191, v66, v219
	s_addc_u32 s11, s11, 0
	s_and_b64 vcc, exec, s[12:13]
	s_cbranch_vccnz .LBB0_2075
	v_mov_b32_e32 v193, v162
	s_branch .LBB0_2063
